# attention fast step: row max via 17 max3/max instead of 57 ops
# speedup vs baseline: 1.0206x; 1.0168x over previous
.LBB0_1352:
	s_waitcnt lgkmcnt(7)
	v_mfma_f32_32x32x16_bf16 v[2:17], v[114:117], v[66:69], 0
	s_waitcnt lgkmcnt(5)
	v_mfma_f32_32x32x16_bf16 v[18:33], v[118:121], v[66:69], 0
	v_mfma_f32_32x32x16_bf16 v[2:17], v[102:105], v[70:73], v[2:17]
	s_waitcnt lgkmcnt(4)
	v_mfma_f32_32x32x16_bf16 v[18:33], v[106:109], v[70:73], v[18:33]
	s_waitcnt lgkmcnt(3)
	v_mfma_f32_32x32x16_bf16 v[2:17], v[98:101], v[74:77], v[2:17]
	s_waitcnt lgkmcnt(1)
	v_mfma_f32_32x32x16_bf16 v[18:33], v[110:113], v[74:77], v[18:33]
	v_mfma_f32_32x32x16_bf16 v[2:17], v[94:97], v[78:81], v[2:17]
	s_waitcnt lgkmcnt(0)
	v_mfma_f32_32x32x16_bf16 v[18:33], v[90:93], v[78:81], v[18:33]
	s_nop 9
	v_max3_f32 v0, v2, v3, s53
	v_max3_f32 v90, v10, v11, v12
	v_max3_f32 v0, v0, v4, v5
	v_max3_f32 v90, v90, v13, v14
	v_max3_f32 v0, v0, v6, v7
	v_max3_f32 v90, v90, v15, v16
	v_max3_f32 v0, v0, v8, v9
	v_max3_f32 v90, v90, v17, v26
	v_max3_f32 v0, v0, v18, v19
	v_max3_f32 v90, v90, v27, v28
	v_max3_f32 v0, v0, v20, v21
	v_max3_f32 v90, v90, v29, v30
	v_max3_f32 v0, v0, v22, v23
	v_max3_f32 v90, v90, v31, v32
	v_max3_f32 v0, v0, v24, v25
	v_max3_f32 v90, v90, v33, v33
	v_max_f32_e32 v0, v0, v90
	v_and_b32_e32 v91, 64, v189
	v_xor_b32_e32 v90, 32, v189
	v_add_u32_e32 v91, 64, v91
	v_cmp_lt_i32_e32 vcc, v90, v91
	v_cndmask_b32_e64 v0, v0, v190, s[22:23]
	s_nop 0
	v_cndmask_b32_e32 v90, v189, v90, vcc
	v_lshlrev_b32_e32 v90, 2, v90
	ds_bpermute_b32 v90, v90, v0
	s_waitcnt lgkmcnt(0)
	v_max3_f32 v0, v224, v0, v90
	v_cndmask_b32_e64 v102, v0, v191, s[22:23]
	v_pk_add_f32 v[2:3], v[2:3], v[102:103] op_sel_hi:[1,0] neg_lo:[0,1] neg_hi:[0,1]
	v_pk_add_f32 v[18:19], v[18:19], v[102:103] op_sel_hi:[1,0] neg_lo:[0,1] neg_hi:[0,1]
	v_exp_f32_e32 v114, v2
	v_exp_f32_e32 v115, v3
	v_exp_f32_e32 v92, v18
	v_exp_f32_e32 v93, v19
	v_pk_add_f32 v[4:5], v[4:5], v[102:103] op_sel_hi:[1,0] neg_lo:[0,1] neg_hi:[0,1]
	v_pk_add_f32 v[18:19], v[20:21], v[102:103] op_sel_hi:[1,0] neg_lo:[0,1] neg_hi:[0,1]
	v_exp_f32_e32 v116, v4
	v_exp_f32_e32 v117, v5
	v_exp_f32_e32 v94, v18
	v_exp_f32_e32 v95, v19
	v_pk_add_f32 v[4:5], v[6:7], v[102:103] op_sel_hi:[1,0] neg_lo:[0,1] neg_hi:[0,1]
	v_pk_add_f32 v[2:3], v[114:115], 0 op_sel_hi:[1,0]
	v_pk_add_f32 v[6:7], v[22:23], v[102:103] op_sel_hi:[1,0] neg_lo:[0,1] neg_hi:[0,1]
	v_exp_f32_e32 v118, v4
	v_exp_f32_e32 v119, v5
	v_pk_add_f32 v[2:3], v[92:93], v[2:3]
	v_exp_f32_e32 v98, v6
	v_exp_f32_e32 v99, v7
	v_pk_add_f32 v[4:5], v[8:9], v[102:103] op_sel_hi:[1,0] neg_lo:[0,1] neg_hi:[0,1]
	v_pk_add_f32 v[2:3], v[116:117], v[2:3]
	v_pk_add_f32 v[6:7], v[24:25], v[102:103] op_sel_hi:[1,0] neg_lo:[0,1] neg_hi:[0,1]
	v_exp_f32_e32 v120, v4
	v_exp_f32_e32 v121, v5
	v_pk_add_f32 v[2:3], v[94:95], v[2:3]
	v_exp_f32_e32 v104, v6
	v_exp_f32_e32 v105, v7
	v_pk_add_f32 v[4:5], v[10:11], v[102:103] op_sel_hi:[1,0] neg_lo:[0,1] neg_hi:[0,1]
	v_pk_add_f32 v[2:3], v[118:119], v[2:3]
	v_pk_add_f32 v[6:7], v[26:27], v[102:103] op_sel_hi:[1,0] neg_lo:[0,1] neg_hi:[0,1]
	v_exp_f32_e32 v106, v4
	v_exp_f32_e32 v107, v5
	v_pk_add_f32 v[2:3], v[98:99], v[2:3]
	v_exp_f32_e32 v90, v6
	v_exp_f32_e32 v91, v7
	v_pk_add_f32 v[4:5], v[12:13], v[102:103] op_sel_hi:[1,0] neg_lo:[0,1] neg_hi:[0,1]
	v_pk_add_f32 v[2:3], v[120:121], v[2:3]
	v_pk_add_f32 v[6:7], v[28:29], v[102:103] op_sel_hi:[1,0] neg_lo:[0,1] neg_hi:[0,1]
	v_exp_f32_e32 v108, v4
	v_exp_f32_e32 v109, v5
	v_pk_add_f32 v[2:3], v[104:105], v[2:3]
	v_exp_f32_e32 v96, v6
	v_exp_f32_e32 v97, v7
	v_pk_add_f32 v[4:5], v[14:15], v[102:103] op_sel_hi:[1,0] neg_lo:[0,1] neg_hi:[0,1]
	v_pk_add_f32 v[2:3], v[106:107], v[2:3]
	v_pk_add_f32 v[6:7], v[30:31], v[102:103] op_sel_hi:[1,0] neg_lo:[0,1] neg_hi:[0,1]
	v_exp_f32_e32 v110, v4
	v_exp_f32_e32 v111, v5
	v_pk_add_f32 v[2:3], v[90:91], v[2:3]
	v_exp_f32_e32 v100, v6
	v_exp_f32_e32 v101, v7
	v_pk_add_f32 v[4:5], v[16:17], v[102:103] op_sel_hi:[1,0] neg_lo:[0,1] neg_hi:[0,1]
	v_pk_add_f32 v[2:3], v[108:109], v[2:3]
	v_pk_add_f32 v[6:7], v[32:33], v[102:103] op_sel_hi:[1,0] neg_lo:[0,1] neg_hi:[0,1]
	v_exp_f32_e32 v112, v4
	v_exp_f32_e32 v113, v5
	v_sub_f32_e32 v174, v224, v0
	v_pk_add_f32 v[2:3], v[96:97], v[2:3]
	v_exp_f32_e32 v102, v6
	v_exp_f32_e32 v103, v7
	v_pk_add_f32 v[2:3], v[110:111], v[2:3]
	v_exp_f32_e32 v18, v174
	v_pk_add_f32 v[2:3], v[100:101], v[2:3]
	v_pk_mul_f32 v[24:25], v[40:41], v[18:19] op_sel_hi:[1,0]
	v_pk_add_f32 v[2:3], v[112:113], v[2:3]
	v_pk_mul_f32 v[22:23], v[38:39], v[18:19] op_sel_hi:[1,0]
	v_pk_add_f32 v[2:3], v[102:103], v[2:3]
	v_pk_mul_f32 v[32:33], v[48:49], v[18:19] op_sel_hi:[1,0]
	v_add_f32_e32 v174, v2, v3
	v_pk_mul_f32 v[2:3], v[50:51], v[18:19] op_sel_hi:[1,0]
	v_add_u32_e32 v50, 0x5800, v222
	ds_read2_b64 v[38:41], v50 offset0:32 offset1:34
	v_add_u32_e32 v51, 0x4800, v222
	v_pk_mul_f32 v[30:31], v[46:47], v[18:19] op_sel_hi:[1,0]
	v_pk_mul_f32 v[28:29], v[44:45], v[18:19] op_sel_hi:[1,0]
	v_pk_mul_f32 v[26:27], v[42:43], v[18:19] op_sel_hi:[1,0]
	ds_read2_b64 v[42:45], v51 offset1:2
	ds_read2_b64 v[46:49], v51 offset0:4 offset1:6
	v_fmac_f32_e32 v174, v223, v18
	v_pk_mul_f32 v[16:17], v[64:65], v[18:19] op_sel_hi:[1,0]
	v_pk_mul_f32 v[14:15], v[62:63], v[18:19] op_sel_hi:[1,0]
	v_pk_mul_f32 v[12:13], v[60:61], v[18:19] op_sel_hi:[1,0]
	v_pk_mul_f32 v[10:11], v[58:59], v[18:19] op_sel_hi:[1,0]
	v_pk_mul_f32 v[8:9], v[56:57], v[18:19] op_sel_hi:[1,0]
	v_pk_mul_f32 v[6:7], v[54:55], v[18:19] op_sel_hi:[1,0]
	v_pk_mul_f32 v[4:5], v[52:53], v[18:19] op_sel_hi:[1,0]
	v_pk_mul_f32 v[20:21], v[36:37], v[18:19] op_sel_hi:[1,0]
	v_pk_mul_f32 v[18:19], v[34:35], v[18:19] op_sel_hi:[1,0]
	v_cvt_pk_bf16_f32 v34, v114, v115
	v_cvt_pk_bf16_f32 v35, v116, v117
	v_cvt_pk_bf16_f32 v36, v118, v119
	v_cvt_pk_bf16_f32 v37, v120, v121
	s_waitcnt lgkmcnt(2)
	s_nop 0
	v_mfma_f32_32x32x16_bf16 v[18:33], v[38:41], v[34:37], v[18:33]
	ds_read2_b64 v[38:41], v50 offset0:36 offset1:38
	s_waitcnt lgkmcnt(2)
	v_mfma_f32_32x32x16_bf16 v[2:17], v[42:45], v[34:37], v[2:17]
	v_cvt_pk_bf16_f32 v34, v106, v107
	v_cvt_pk_bf16_f32 v35, v108, v109
	v_cvt_pk_bf16_f32 v36, v110, v111
	v_cvt_pk_bf16_f32 v37, v112, v113
	s_waitcnt lgkmcnt(1)
	s_nop 0
	v_mfma_f32_32x32x16_bf16 v[2:17], v[46:49], v[34:37], v[2:17]
	s_waitcnt lgkmcnt(0)
	v_mfma_f32_32x32x16_bf16 v[18:33], v[38:41], v[34:37], v[18:33]
	ds_read2_b64 v[38:41], v51 offset0:8 offset1:10
	ds_read2_b64 v[42:45], v50 offset0:40 offset1:42
	v_cvt_pk_bf16_f32 v34, v92, v93
	v_cvt_pk_bf16_f32 v35, v94, v95
	v_cvt_pk_bf16_f32 v36, v98, v99
	v_cvt_pk_bf16_f32 v37, v104, v105
	s_waitcnt lgkmcnt(1)
	s_nop 0
	v_mfma_f32_32x32x16_bf16 v[2:17], v[38:41], v[34:37], v[2:17]
	s_waitcnt lgkmcnt(0)
	v_mfma_f32_32x32x16_bf16 v[18:33], v[42:45], v[34:37], v[18:33]
	ds_read2_b64 v[38:41], v51 offset0:12 offset1:14
	ds_read2_b64 v[42:45], v50 offset0:44 offset1:46
	v_cvt_pk_bf16_f32 v34, v90, v91
	v_cvt_pk_bf16_f32 v35, v96, v97
	v_cvt_pk_bf16_f32 v36, v100, v101
	v_cvt_pk_bf16_f32 v37, v102, v103
	s_waitcnt lgkmcnt(1)
	s_nop 0
	v_mfma_f32_32x32x16_bf16 v[2:17], v[38:41], v[34:37], v[2:17]
	s_waitcnt lgkmcnt(0)
	v_mfma_f32_32x32x16_bf16 v[18:33], v[42:45], v[34:37], v[18:33]
